# stack on k17: P0 next-tile loads made a real prefetch, x/mem conversion loops with 8/4 loads in flight, MoE-up next-tile row-list gathers hoisted above the epilogue stores
# speedup vs baseline: 1.0103x; 1.0024x over previous
.LBB0_49:
	s_or_b64 exec, exec, s[40:41]
	s_waitcnt lgkmcnt(0)
	s_ashr_i32 s27, s26, 31
	s_cmpk_gt_i32 s2, 0x6c7f
	s_cbranch_scc1 .LBB0_106
	v_mov_b32_e32 v14, s38
	v_mov_b32_e32 v15, s39
	v_mov_b32_e32 v7, 0
	s_movk_i32 s48, 0x104
	s_movk_i32 s49, 0xffc0
	s_mov_b32 s50, s2
	s_waitcnt vmcnt(0)
	s_branch .LBB0_53

.LBB0_52:
	s_or_b64 exec, exec, s[42:43]
	v_lshlrev_b32_e32 v4, 3, v6
	v_and_b32_e32 v6, 24, v4
	v_mul_u32_u24_e32 v4, 0x104, v6
	v_lshl_add_u32 v3, v3, 2, v4
	ds_read2_b32 v[4:5], v3 offset1:65
	ds_read2_b32 v[10:11], v3 offset0:130 offset1:195
	v_add_u32_e32 v8, 0x400, v3
	ds_read2_b32 v[12:13], v8 offset0:4 offset1:69
	ds_read2_b32 v[16:17], v8 offset0:134 offset1:199
	v_ashrrev_i32_e32 v18, 31, v1
	s_waitcnt lgkmcnt(3)
	v_cvt_pk_bf16_f32 v8, v4, v5
	s_waitcnt lgkmcnt(2)
	v_cvt_pk_bf16_f32 v9, v10, v11
	s_waitcnt lgkmcnt(1)
	v_cvt_pk_bf16_f32 v10, v12, v13
	v_mul_lo_u32 v12, s37, v1
	v_mul_lo_u32 v13, s36, v18
	v_mad_u64_u32 v[4:5], s[36:37], s36, v1, 0
	v_add_u32_e32 v1, 0x2000, v3
	s_waitcnt lgkmcnt(0)
	v_cvt_pk_bf16_f32 v11, v16, v17
	v_add3_u32 v5, v5, v13, v12
	ds_read2_b32 v[12:13], v1 offset0:32 offset1:97
	ds_read2_b32 v[16:17], v1 offset0:162 offset1:227
	v_add_u32_e32 v1, 0x2400, v3
	ds_read2_b32 v[18:19], v1 offset0:36 offset1:101
	ds_read2_b32 v[20:21], v1 offset0:166 offset1:231
	s_lshl_b32 s42, s47, 6
	s_ashr_i32 s43, s42, 31
	v_lshl_add_u64 v[4:5], v[4:5], 1, s[34:35]
	v_lshl_add_u64 v[4:5], s[42:43], 1, v[4:5]
	v_lshlrev_b32_e32 v6, 1, v6
	v_lshl_add_u64 v[4:5], v[4:5], 0, v[6:7]
	global_store_dwordx4 v[4:5], v[8:11], off
	s_cmpk_lt_i32 s50, 0x6c80
	s_waitcnt vmcnt(1)
	v_mov_b32_e32 v1, v25
	s_waitcnt lgkmcnt(3)
	v_cvt_pk_bf16_f32 v8, v12, v13
	s_waitcnt lgkmcnt(2)
	v_cvt_pk_bf16_f32 v9, v16, v17
	s_waitcnt lgkmcnt(1)
	v_cvt_pk_bf16_f32 v10, v18, v19
	s_waitcnt lgkmcnt(0)
	v_cvt_pk_bf16_f32 v11, v20, v21
	global_store_dwordx4 v[4:5], v[8:11], off offset:64
	v_mov_b32_e32 v3, v26
	v_mov_b32_e32 v5, v24
	v_mov_b32_e32 v4, v27
	v_mov_b32_e32 v11, v29
	v_mov_b32_e32 v12, v30
	v_mov_b32_e32 v10, v28
	v_mov_b32_e32 v13, v31
	v_mov_b32_e32 v17, v33
	v_mov_b32_e32 v18, v34
	v_mov_b32_e32 v16, v32
	v_mov_b32_e32 v19, v36
	v_mov_b32_e32 v21, v38
	v_mov_b32_e32 v22, v39
	v_mov_b32_e32 v20, v37
	v_mov_b32_e32 v23, v40
	s_mov_b32 s46, s53
	s_mov_b32 s47, s54
	s_mov_b32 s33, s52
	s_mov_b64 s[36:37], s[40:41]
	s_mov_b64 s[34:35], s[38:39]
	s_mov_b32 s3, s51
	s_barrier
	s_cbranch_scc0 .LBB0_106

.LBB0_100:
	s_or_b64 exec, exec, s[42:43]
	v_mov_b32_e32 v6, v216
	s_lshr_b32 s42, s47, 6
	v_ashrrev_i32_e32 v9, 6, v6
	v_and_b32_e32 v8, 63, v6
	v_mul_lo_u32 v9, v9, s48
	v_lshl_add_u32 v8, v8, 2, v9
	s_nop 0
	ds_write_b32 v8, v1
	s_nop 0
	ds_write_b32 v8, v3 offset:1040
	ds_write_b32 v8, v5 offset:2080
	ds_write_b32 v8, v4 offset:3120
	ds_write_b32 v8, v11 offset:4160
	ds_write_b32 v8, v12 offset:5200
	ds_write_b32 v8, v10 offset:6240
	ds_write_b32 v8, v13 offset:7280
	ds_write_b32 v8, v17 offset:8320
	ds_write_b32 v8, v18 offset:9360
	v_cvt_f32_u32_e32 v1, s42
	s_sub_i32 s45, 0, s42
	s_abs_i32 s44, s3
	s_ashr_i32 s43, s3, 31
	v_rcp_iflag_f32_e32 v1, v1
	v_ashrrev_i32_e32 v3, 2, v6
	ds_write_b32 v8, v16 offset:10400
	ds_write_b32 v8, v19 offset:11440
	ds_write_b32 v8, v21 offset:12480
	ds_write_b32 v8, v22 offset:13520
	ds_write_b32 v8, v20 offset:14560
	ds_write_b32 v8, v23 offset:15600
	v_mul_f32_e32 v1, 0x4f7ffffe, v1
	v_cvt_u32_f32_e32 v1, v1
	s_waitcnt lgkmcnt(0)
	s_barrier
	v_readfirstlane_b32 s47, v1
	s_mul_i32 s45, s45, s47
	s_mul_hi_u32 s45, s47, s45
	s_add_i32 s47, s47, s45
	s_mul_hi_u32 s45, s44, s47
	s_mul_i32 s47, s45, s42
	s_sub_i32 s44, s44, s47
	s_add_i32 s47, s45, 1
	s_sub_i32 s55, s44, s42
	s_cmp_ge_u32 s44, s42
	s_cselect_b32 s45, s47, s45
	s_cselect_b32 s44, s55, s44
	s_add_i32 s47, s45, 1
	s_cmp_ge_u32 s44, s42
	s_cselect_b32 s44, s47, s45
	s_xor_b32 s44, s44, s43
	s_sub_i32 s47, s44, s43
	s_mul_i32 s42, s47, s42
	s_sub_i32 s3, s3, s42
	v_lshl_add_u32 v1, s3, 6, v3
	s_cmp_lg_u32 s46, 0
	v_cmp_gt_i32_e32 vcc, s33, v1
	s_cselect_b64 s[42:43], -1, 0
	s_and_b64 s[44:45], s[42:43], vcc
	s_and_saveexec_b64 s[42:43], s[44:45]
	s_cbranch_execz .LBB0_52
	s_lshr_b32 s3, s33, 1
	v_cmp_le_i32_e32 vcc, s3, v1
	s_and_saveexec_b64 s[44:45], vcc
	s_xor_b64 s[44:45], exec, s[44:45]
	v_subrev_u32_e32 v1, s3, v1
	v_lshlrev_b32_e32 v4, 1, v1
	v_and_b32_e32 v4, 0x7fffffc0, v4
	v_and_b32_e32 v1, 31, v1
	v_or3_b32 v1, v1, v4, 32
	s_andn2_saveexec_b64 s[44:45], s[44:45]
	s_cbranch_execz .LBB0_51
	v_lshlrev_b32_e32 v1, 1, v1
	v_bfe_u32 v4, v6, 2, 5
	v_and_or_b32 v1, v1, s49, v4
	s_branch .LBB0_51

.LBB0_892:
	s_or_b64 exec, exec, s[0:1]
	v_readlane_b32 s2, v255, 38
	v_readlane_b32 s3, v255, 39
	s_mov_b64 s[0:1], -1
	s_and_b64 vcc, exec, s[2:3]
	s_barrier
	s_cbranch_vccz .LBB0_989
	v_readlane_b32 s0, v254, 45
	v_readlane_b32 s6, v254, 51
	v_readlane_b32 s7, v254, 52
	v_readlane_b32 s1, v254, 46
	v_mov_b32_e32 v1, s6
	v_mov_b32_e32 v0, s7
	v_readlane_b32 s2, v254, 47
	v_readlane_b32 s3, v254, 48
	v_readfirstlane_b32 s0, v1
	v_readfirstlane_b32 s1, v0
	s_add_u32 s2, s0, 0x1d200020
	s_addc_u32 s3, s1, 0
	s_nop 0
	global_load_dwordx4 v[0:3], v179, s[2:3] offset:16
	s_nop 0
	global_load_dwordx4 v[4:7], v219, s[0:1] offset:32
	v_mov_b32_e32 v8, s6
	v_mov_b32_e32 v9, s7
	v_readlane_b32 s4, v254, 49
	v_readlane_b32 s5, v254, 50
	v_mov_b32_e32 v10, v216
	s_waitcnt vmcnt(1)
	v_readfirstlane_b32 s2, v0
	s_waitcnt vmcnt(0)
	v_readfirstlane_b32 s6, v4
	v_readfirstlane_b32 s7, v5
	v_readfirstlane_b32 s8, v6
	s_add_i32 s0, s6, 0x7f
	s_add_i32 s1, s7, 0x7f
	v_readfirstlane_b32 s9, v7
	s_add_i32 s10, s8, 0x7f
	s_ashr_i32 s16, s0, 7
	s_ashr_i32 s17, s1, 7
	s_add_i32 s11, s9, 0x7f
	s_and_b32 s18, s0, 0xffffff80
	s_ashr_i32 s10, s10, 7
	s_add_i32 s0, s17, s16
	v_readfirstlane_b32 s3, v1
	s_add_i32 s12, s2, 0x7f
	s_ashr_i32 s11, s11, 7
	s_lshl_b32 s19, s0, 7
	s_add_i32 s0, s10, s0
	v_readfirstlane_b32 s4, v2
	s_add_i32 s13, s3, 0x7f
	s_ashr_i32 s12, s12, 7
	s_lshl_b32 s20, s0, 7
	s_add_i32 s0, s11, s0
	s_add_i32 s14, s4, 0x7f
	s_ashr_i32 s13, s13, 7
	s_lshl_b32 s22, s0, 7
	s_add_i32 s0, s12, s0
	s_ashr_i32 s14, s14, 7
	s_lshl_b32 s23, s0, 7
	s_add_i32 s0, s13, s0
	v_readfirstlane_b32 s5, v3
	s_lshl_b32 s24, s0, 7
	s_add_i32 s0, s14, s0
	s_add_i32 s15, s5, 0x7f
	s_lshl_b32 s25, s0, 7
	v_readlane_b32 s0, v254, 15
	s_ashr_i32 s15, s15, 7
	v_readlane_b32 s1, v254, 16
	s_and_b64 s[0:1], s[0:1], exec
	v_readlane_b32 s0, v254, 17
	v_readlane_b32 s1, v254, 18
	s_cselect_b32 s6, s6, 0
	s_cselect_b32 s16, s16, 0
	s_and_b64 s[0:1], s[0:1], exec
	v_readlane_b32 s0, v254, 19
	v_readlane_b32 s1, v254, 20
	s_cselect_b32 s6, s7, s6
	s_cselect_b32 s7, s17, s16
	s_cselect_b32 s16, s18, 0
	s_and_b64 s[0:1], s[0:1], exec
	v_readlane_b32 s0, v254, 21
	v_readlane_b32 s1, v254, 22
	s_cselect_b32 s6, s8, s6
	s_cselect_b32 s7, s10, s7
	s_cselect_b32 s8, s19, s16
	s_and_b64 s[0:1], s[0:1], exec
	v_readlane_b32 s0, v254, 23
	v_readlane_b32 s1, v254, 24
	s_cselect_b32 s6, s9, s6
	s_cselect_b32 s7, s11, s7
	s_cselect_b32 s8, s20, s8
	s_and_b64 s[0:1], s[0:1], exec
	v_readlane_b32 s0, v254, 25
	v_readlane_b32 s1, v254, 26
	s_cselect_b32 s2, s2, s6
	s_cselect_b32 s6, s12, s7
	s_cselect_b32 s7, s22, s8
	s_and_b64 s[0:1], s[0:1], exec
	v_readlane_b32 s0, v254, 27
	v_readlane_b32 s1, v254, 28
	s_cselect_b32 s2, s3, s2
	s_cselect_b32 s3, s13, s6
	s_cselect_b32 s6, s23, s7
	s_and_b64 s[0:1], s[0:1], exec
	v_readlane_b32 s0, v254, 29
	v_readlane_b32 s1, v254, 30
	s_cselect_b32 s2, s4, s2
	s_cselect_b32 s3, s14, s3
	s_cselect_b32 s4, s24, s6
	s_and_b64 s[0:1], s[0:1], exec
	s_cselect_b32 s17, s15, s3
	v_readfirstlane_b32 s21, v8
	s_cselect_b32 s16, s5, s2
	s_cselect_b32 s18, s25, s4
	s_cmp_gt_i32 s17, 0
	v_readfirstlane_b32 s22, v9
	s_cbranch_scc0 .LBB0_916
	s_add_u32 s4, s21, 0x1d222100
	s_addc_u32 s5, s22, 0
	s_add_u32 s23, s21, 0x1d100000
	s_mul_i32 s0, s17, 28
	v_readlane_b32 s1, v254, 31
	s_addc_u32 s24, s22, 0
	s_mul_hi_u32 s1, s0, s1
	v_readlane_b32 s3, v254, 32
	s_add_u32 s6, s21, 0xd900000
	s_mul_i32 s1, s1, s3
	s_addc_u32 s7, s22, 0
	s_sub_i32 s1, s0, s1
	s_lshl_b32 s19, s17, 2
	s_sub_i32 s2, s1, s3
	s_cmp_ge_u32 s1, s3
	s_cselect_b32 s1, s2, s1
	s_sub_i32 s2, s1, s3
	s_cmp_ge_u32 s1, s3
	s_cselect_b32 s25, s2, s1
	s_sub_i32 s20, s0, s25
	s_mul_i32 s0, s33, 0xe00000
	s_add_u32 s0, s21, s0
	s_addc_u32 s1, s22, 0
	s_add_u32 s8, s0, 0x3100000
	s_addc_u32 s9, s1, 0
	s_cmp_ge_i32 s47, s20
	s_cbranch_scc1 .LBB0_905
	v_readlane_b32 s0, v254, 2
	s_add_u32 s0, s23, s0
	s_addc_u32 s1, s24, 0
	s_abs_i32 s26, s19
	v_cvt_f32_u32_e32 v0, s26
	s_sub_i32 s2, 0, s26
	s_add_i32 s27, s16, -1
	s_ashr_i32 s28, s19, 31
	v_rcp_iflag_f32_e32 v0, v0
	s_mov_b32 s30, s47
	v_mul_f32_e32 v0, 0x4f7ffffe, v0
	v_cvt_u32_f32_e32 v0, v0
	s_nop 0
	v_readfirstlane_b32 s3, v0
	s_mul_i32 s2, s2, s3
	s_mul_hi_u32 s2, s3, s2
	s_add_i32 s29, s3, s2
	v_readlane_b32 s2, v254, 39
	s_add_u32 s10, s21, s2
	v_readlane_b32 s2, v254, 40
	s_addc_u32 s11, s22, s2
	s_abs_i32 s3, s30
	s_mul_hi_u32 s12, s3, s29
	s_mul_i32 s13, s12, s26
	s_ashr_i32 s2, s30, 31
	s_sub_i32 s3, s3, s13
	s_xor_b32 s2, s2, s28
	s_add_i32 s13, s12, 1
	s_sub_i32 s14, s3, s26
	s_cmp_ge_u32 s3, s26
	s_cselect_b32 s12, s13, s12
	s_cselect_b32 s3, s14, s3
	s_add_i32 s13, s12, 1
	s_cmp_ge_u32 s3, s26
	s_cselect_b32 s3, s13, s12
	s_xor_b32 s3, s3, s2
	s_sub_i32 s2, s3, s2
	s_mul_i32 s3, s2, s19
	s_sub_i32 s3, s30, s3
	s_lshl_b32 s12, s3, 5
	s_and_b32 s14, s12, 0xffffff80
	v_ashrrev_i32_e32 v155, 2, v216
	v_add_u32_e32 v155, s14, v155
	v_min_i32_e32 v156, s27, v155
	v_ashrrev_i32_e32 v157, 31, v156
	v_lshl_add_u64 v[156:157], v[156:157], 2, s[0:1]
	global_load_dword v163, v[156:157], off
	v_add_u32_e32 v158, 64, v155
	v_min_i32_e32 v158, s27, v158
	v_ashrrev_i32_e32 v159, 31, v158
	v_lshl_add_u64 v[158:159], v[158:159], 2, s[0:1]
	global_load_dword v164, v[158:159], off
	s_waitcnt vmcnt(0)
	s_branch .LBB0_897
.LBB0_896:
	v_or_b32_e32 v128, s34, v185
	v_lshrrev_b32_e32 v129, 3, v181
	v_ashrrev_i32_e32 v128, 1, v128
	v_and_b32_e32 v129, 4, v129
	s_add_i32 s31, s31, s18
	v_or_b32_e32 v128, v128, v183
	v_add3_u32 v130, s31, v189, v129
	v_lshlrev_b32_e32 v128, 1, v128
	v_mad_u32_u24 v128, v130, s88, v128
	s_nop 7
	s_nop 7
	s_nop 3
	s_add_i32 s35, s30, s85
	s_abs_i32 s3, s35
	s_mul_hi_u32 s12, s3, s29
	s_mul_i32 s13, s12, s26
	s_ashr_i32 s2, s35, 31
	s_sub_i32 s3, s3, s13
	s_xor_b32 s2, s2, s28
	s_add_i32 s13, s12, 1
	s_sub_i32 s14, s3, s26
	s_cmp_ge_u32 s3, s26
	s_cselect_b32 s12, s13, s12
	s_cselect_b32 s3, s14, s3
	s_add_i32 s13, s12, 1
	s_cmp_ge_u32 s3, s26
	s_cselect_b32 s3, s13, s12
	s_xor_b32 s3, s3, s2
	s_sub_i32 s2, s3, s2
	s_mul_i32 s3, s2, s19
	s_sub_i32 s3, s35, s3
	s_lshl_b32 s12, s3, 5
	s_and_b32 s14, s12, 0xffffff80
	v_ashrrev_i32_e32 v155, 2, v216
	v_add_u32_e32 v155, s14, v155
	v_min_i32_e32 v156, s27, v155
	v_ashrrev_i32_e32 v157, 31, v156
	v_lshl_add_u64 v[156:157], v[156:157], 2, s[0:1]
	global_load_dword v163, v[156:157], off
	v_add_u32_e32 v158, 64, v155
	v_min_i32_e32 v158, s27, v158
	v_ashrrev_i32_e32 v159, 31, v158
	v_lshl_add_u64 v[158:159], v[158:159], 2, s[0:1]
	global_load_dword v164, v[158:159], off
	v_mul_f32_e32 v131, 0xbfb8aa3b, v112
	v_mul_f32_e32 v132, 0xbfb8aa3b, v113
	v_mul_f32_e32 v133, 0xbfb8aa3b, v114
	v_mul_f32_e32 v134, 0xbfb8aa3b, v115
	v_mul_f32_e32 v135, 0xbfb8aa3b, v116
	v_mul_f32_e32 v136, 0xbfb8aa3b, v117
	v_mul_f32_e32 v137, 0xbfb8aa3b, v118
	v_mul_f32_e32 v138, 0xbfb8aa3b, v119
	v_exp_f32_e32 v131, v131
	v_exp_f32_e32 v132, v132
	v_exp_f32_e32 v133, v133
	v_exp_f32_e32 v134, v134
	v_exp_f32_e32 v135, v135
	v_exp_f32_e32 v136, v136
	v_exp_f32_e32 v137, v137
	v_exp_f32_e32 v138, v138
	v_add_f32_e32 v131, 1.0, v131
	v_add_f32_e32 v132, 1.0, v132
	v_add_f32_e32 v133, 1.0, v133
	v_add_f32_e32 v134, 1.0, v134
	v_add_f32_e32 v135, 1.0, v135
	v_add_f32_e32 v136, 1.0, v136
	v_add_f32_e32 v137, 1.0, v137
	v_add_f32_e32 v138, 1.0, v138
	v_rcp_f32_e32 v131, v131
	v_rcp_f32_e32 v132, v132
	v_rcp_f32_e32 v133, v133
	v_rcp_f32_e32 v134, v134
	v_rcp_f32_e32 v135, v135
	v_rcp_f32_e32 v136, v136
	v_rcp_f32_e32 v137, v137
	v_rcp_f32_e32 v138, v138
	v_mul_f32_e32 v131, v112, v131
	v_mul_f32_e32 v132, v113, v132
	v_mul_f32_e32 v133, v114, v133
	v_mul_f32_e32 v134, v115, v134
	v_mul_f32_e32 v135, v116, v135
	v_mul_f32_e32 v136, v117, v136
	v_mul_f32_e32 v137, v118, v137
	v_mul_f32_e32 v138, v119, v138
	v_mul_f32_e32 v131, v96, v131
	v_mul_f32_e32 v132, v97, v132
	v_mul_f32_e32 v133, v98, v133
	v_mul_f32_e32 v134, v99, v134
	v_mul_f32_e32 v135, v100, v135
	v_mul_f32_e32 v136, v101, v136
	v_mul_f32_e32 v137, v102, v137
	v_mul_f32_e32 v138, v103, v138
	v_add_u32_e32 v112, 0, v128
	v_add_u32_e32 v113, 0x1c00, v128
	v_add_u32_e32 v114, 0x3800, v128
	v_add_u32_e32 v115, 0x5400, v128
	v_add_u32_e32 v116, 0xe000, v128
	v_add_u32_e32 v117, 0xfc00, v128
	v_add_u32_e32 v118, 0x11800, v128
	v_add_u32_e32 v119, 0x13400, v128
	v_cvt_pk_bf16_f32 v139, v131, v132
	v_cvt_pk_bf16_f32 v140, v133, v134
	v_cvt_pk_bf16_f32 v141, v135, v136
	v_cvt_pk_bf16_f32 v142, v137, v138
	global_store_short v112, v139, s[4:5]
	global_store_short_d16_hi v113, v139, s[4:5]
	global_store_short v114, v140, s[4:5]
	global_store_short_d16_hi v115, v140, s[4:5]
	global_store_short v116, v141, s[4:5]
	global_store_short_d16_hi v117, v141, s[4:5]
	global_store_short v118, v142, s[4:5]
	global_store_short_d16_hi v119, v142, s[4:5]
	v_mul_f32_e32 v143, 0xbfb8aa3b, v120
	v_mul_f32_e32 v144, 0xbfb8aa3b, v121
	v_mul_f32_e32 v145, 0xbfb8aa3b, v122
	v_mul_f32_e32 v146, 0xbfb8aa3b, v123
	v_mul_f32_e32 v147, 0xbfb8aa3b, v124
	v_mul_f32_e32 v148, 0xbfb8aa3b, v125
	v_mul_f32_e32 v149, 0xbfb8aa3b, v126
	v_mul_f32_e32 v150, 0xbfb8aa3b, v127
	v_exp_f32_e32 v143, v143
	v_exp_f32_e32 v144, v144
	v_exp_f32_e32 v145, v145
	v_exp_f32_e32 v146, v146
	v_exp_f32_e32 v147, v147
	v_exp_f32_e32 v148, v148
	v_exp_f32_e32 v149, v149
	v_exp_f32_e32 v150, v150
	v_add_f32_e32 v143, 1.0, v143
	v_add_f32_e32 v144, 1.0, v144
	v_add_f32_e32 v145, 1.0, v145
	v_add_f32_e32 v146, 1.0, v146
	v_add_f32_e32 v147, 1.0, v147
	v_add_f32_e32 v148, 1.0, v148
	v_add_f32_e32 v149, 1.0, v149
	v_add_f32_e32 v150, 1.0, v150
	v_rcp_f32_e32 v143, v143
	v_rcp_f32_e32 v144, v144
	v_rcp_f32_e32 v145, v145
	v_rcp_f32_e32 v146, v146
	v_rcp_f32_e32 v147, v147
	v_rcp_f32_e32 v148, v148
	v_rcp_f32_e32 v149, v149
	v_rcp_f32_e32 v150, v150
	v_mul_f32_e32 v143, v120, v143
	v_mul_f32_e32 v144, v121, v144
	v_mul_f32_e32 v145, v122, v145
	v_mul_f32_e32 v146, v123, v146
	v_mul_f32_e32 v147, v124, v147
	v_mul_f32_e32 v148, v125, v148
	v_mul_f32_e32 v149, v126, v149
	v_mul_f32_e32 v150, v127, v150
	v_mul_f32_e32 v143, v104, v143
	v_mul_f32_e32 v144, v105, v144
	v_mul_f32_e32 v145, v106, v145
	v_mul_f32_e32 v146, v107, v146
	v_mul_f32_e32 v147, v108, v147
	v_mul_f32_e32 v148, v109, v148
	v_mul_f32_e32 v149, v110, v149
	v_mul_f32_e32 v150, v111, v150
	v_add_u32_e32 v120, 0x1c000, v128
	v_add_u32_e32 v121, 0x1dc00, v128
	v_add_u32_e32 v122, 0x1f800, v128
	v_add_u32_e32 v123, 0x21400, v128
	v_add_u32_e32 v124, 0x2a000, v128
	v_add_u32_e32 v125, 0x2bc00, v128
	v_add_u32_e32 v126, 0x2d800, v128
	v_add_u32_e32 v127, 0x2f400, v128
	v_cvt_pk_bf16_f32 v151, v143, v144
	v_cvt_pk_bf16_f32 v152, v145, v146
	v_cvt_pk_bf16_f32 v153, v147, v148
	v_cvt_pk_bf16_f32 v154, v149, v150
	global_store_short v120, v151, s[4:5]
	global_store_short_d16_hi v121, v151, s[4:5]
	global_store_short v122, v152, s[4:5]
	global_store_short_d16_hi v123, v152, s[4:5]
	global_store_short v124, v153, s[4:5]
	global_store_short_d16_hi v125, v153, s[4:5]
	global_store_short v126, v154, s[4:5]
	global_store_short_d16_hi v127, v154, s[4:5]
	v_mul_f32_e32 v131, 0xbfb8aa3b, v80
	v_mul_f32_e32 v132, 0xbfb8aa3b, v81
	v_mul_f32_e32 v133, 0xbfb8aa3b, v82
	v_mul_f32_e32 v134, 0xbfb8aa3b, v83
	v_mul_f32_e32 v135, 0xbfb8aa3b, v84
	v_mul_f32_e32 v136, 0xbfb8aa3b, v85
	v_mul_f32_e32 v137, 0xbfb8aa3b, v86
	v_mul_f32_e32 v138, 0xbfb8aa3b, v87
	v_exp_f32_e32 v131, v131
	v_exp_f32_e32 v132, v132
	v_exp_f32_e32 v133, v133
	v_exp_f32_e32 v134, v134
	v_exp_f32_e32 v135, v135
	v_exp_f32_e32 v136, v136
	v_exp_f32_e32 v137, v137
	v_exp_f32_e32 v138, v138
	v_add_f32_e32 v131, 1.0, v131
	v_add_f32_e32 v132, 1.0, v132
	v_add_f32_e32 v133, 1.0, v133
	v_add_f32_e32 v134, 1.0, v134
	v_add_f32_e32 v135, 1.0, v135
	v_add_f32_e32 v136, 1.0, v136
	v_add_f32_e32 v137, 1.0, v137
	v_add_f32_e32 v138, 1.0, v138
	v_rcp_f32_e32 v131, v131
	v_rcp_f32_e32 v132, v132
	v_rcp_f32_e32 v133, v133
	v_rcp_f32_e32 v134, v134
	v_rcp_f32_e32 v135, v135
	v_rcp_f32_e32 v136, v136
	v_rcp_f32_e32 v137, v137
	v_rcp_f32_e32 v138, v138
	v_mul_f32_e32 v131, v80, v131
	v_mul_f32_e32 v132, v81, v132
	v_mul_f32_e32 v133, v82, v133
	v_mul_f32_e32 v134, v83, v134
	v_mul_f32_e32 v135, v84, v135
	v_mul_f32_e32 v136, v85, v136
	v_mul_f32_e32 v137, v86, v137
	v_mul_f32_e32 v138, v87, v138
	v_mul_f32_e32 v131, v64, v131
	v_mul_f32_e32 v132, v65, v132
	v_mul_f32_e32 v133, v66, v133
	v_mul_f32_e32 v134, v67, v134
	v_mul_f32_e32 v135, v68, v135
	v_mul_f32_e32 v136, v69, v136
	v_mul_f32_e32 v137, v70, v137
	v_mul_f32_e32 v138, v71, v138
	v_add_u32_e32 v80, 0x38000, v128
	v_add_u32_e32 v81, 0x39c00, v128
	v_add_u32_e32 v82, 0x3b800, v128
	v_add_u32_e32 v83, 0x3d400, v128
	v_add_u32_e32 v84, 0x46000, v128
	v_add_u32_e32 v85, 0x47c00, v128
	v_add_u32_e32 v86, 0x49800, v128
	v_add_u32_e32 v87, 0x4b400, v128
	v_cvt_pk_bf16_f32 v139, v131, v132
	v_cvt_pk_bf16_f32 v140, v133, v134
	v_cvt_pk_bf16_f32 v141, v135, v136
	v_cvt_pk_bf16_f32 v142, v137, v138
	global_store_short v80, v139, s[4:5]
	global_store_short_d16_hi v81, v139, s[4:5]
	global_store_short v82, v140, s[4:5]
	global_store_short_d16_hi v83, v140, s[4:5]
	global_store_short v84, v141, s[4:5]
	global_store_short_d16_hi v85, v141, s[4:5]
	global_store_short v86, v142, s[4:5]
	global_store_short_d16_hi v87, v142, s[4:5]
	v_mul_f32_e32 v143, 0xbfb8aa3b, v88
	v_mul_f32_e32 v144, 0xbfb8aa3b, v89
	v_mul_f32_e32 v145, 0xbfb8aa3b, v90
	v_mul_f32_e32 v146, 0xbfb8aa3b, v91
	v_mul_f32_e32 v147, 0xbfb8aa3b, v92
	v_mul_f32_e32 v148, 0xbfb8aa3b, v93
	v_mul_f32_e32 v149, 0xbfb8aa3b, v94
	v_mul_f32_e32 v150, 0xbfb8aa3b, v95
	v_exp_f32_e32 v143, v143
	v_exp_f32_e32 v144, v144
	v_exp_f32_e32 v145, v145
	v_exp_f32_e32 v146, v146
	v_exp_f32_e32 v147, v147
	v_exp_f32_e32 v148, v148
	v_exp_f32_e32 v149, v149
	v_exp_f32_e32 v150, v150
	v_add_f32_e32 v143, 1.0, v143
	v_add_f32_e32 v144, 1.0, v144
	v_add_f32_e32 v145, 1.0, v145
	v_add_f32_e32 v146, 1.0, v146
	v_add_f32_e32 v147, 1.0, v147
	v_add_f32_e32 v148, 1.0, v148
	v_add_f32_e32 v149, 1.0, v149
	v_add_f32_e32 v150, 1.0, v150
	v_rcp_f32_e32 v143, v143
	v_rcp_f32_e32 v144, v144
	v_rcp_f32_e32 v145, v145
	v_rcp_f32_e32 v146, v146
	v_rcp_f32_e32 v147, v147
	v_rcp_f32_e32 v148, v148
	v_rcp_f32_e32 v149, v149
	v_rcp_f32_e32 v150, v150
	v_mul_f32_e32 v143, v88, v143
	v_mul_f32_e32 v144, v89, v144
	v_mul_f32_e32 v145, v90, v145
	v_mul_f32_e32 v146, v91, v146
	v_mul_f32_e32 v147, v92, v147
	v_mul_f32_e32 v148, v93, v148
	v_mul_f32_e32 v149, v94, v149
	v_mul_f32_e32 v150, v95, v150
	v_mul_f32_e32 v143, v72, v143
	v_mul_f32_e32 v144, v73, v144
	v_mul_f32_e32 v145, v74, v145
	v_mul_f32_e32 v146, v75, v146
	v_mul_f32_e32 v147, v76, v147
	v_mul_f32_e32 v148, v77, v148
	v_mul_f32_e32 v149, v78, v149
	v_mul_f32_e32 v150, v79, v150
	v_add_u32_e32 v88, 0x54000, v128
	v_add_u32_e32 v89, 0x55c00, v128
	v_add_u32_e32 v90, 0x57800, v128
	v_add_u32_e32 v91, 0x59400, v128
	v_add_u32_e32 v92, 0x62000, v128
	v_add_u32_e32 v93, 0x63c00, v128
	v_add_u32_e32 v94, 0x65800, v128
	v_add_u32_e32 v95, 0x67400, v128
	v_cvt_pk_bf16_f32 v151, v143, v144
	v_cvt_pk_bf16_f32 v152, v145, v146
	v_cvt_pk_bf16_f32 v153, v147, v148
	v_cvt_pk_bf16_f32 v154, v149, v150
	global_store_short v88, v151, s[4:5]
	global_store_short_d16_hi v89, v151, s[4:5]
	global_store_short v90, v152, s[4:5]
	global_store_short_d16_hi v91, v152, s[4:5]
	global_store_short v92, v153, s[4:5]
	global_store_short_d16_hi v93, v153, s[4:5]
	global_store_short v94, v154, s[4:5]
	global_store_short_d16_hi v95, v154, s[4:5]
	v_mul_f32_e32 v131, 0xbfb8aa3b, v48
	v_mul_f32_e32 v132, 0xbfb8aa3b, v49
	v_mul_f32_e32 v133, 0xbfb8aa3b, v50
	v_mul_f32_e32 v134, 0xbfb8aa3b, v51
	v_mul_f32_e32 v135, 0xbfb8aa3b, v52
	v_mul_f32_e32 v136, 0xbfb8aa3b, v53
	v_mul_f32_e32 v137, 0xbfb8aa3b, v54
	v_mul_f32_e32 v138, 0xbfb8aa3b, v55
	v_exp_f32_e32 v131, v131
	v_exp_f32_e32 v132, v132
	v_exp_f32_e32 v133, v133
	v_exp_f32_e32 v134, v134
	v_exp_f32_e32 v135, v135
	v_exp_f32_e32 v136, v136
	v_exp_f32_e32 v137, v137
	v_exp_f32_e32 v138, v138
	v_add_f32_e32 v131, 1.0, v131
	v_add_f32_e32 v132, 1.0, v132
	v_add_f32_e32 v133, 1.0, v133
	v_add_f32_e32 v134, 1.0, v134
	v_add_f32_e32 v135, 1.0, v135
	v_add_f32_e32 v136, 1.0, v136
	v_add_f32_e32 v137, 1.0, v137
	v_add_f32_e32 v138, 1.0, v138
	v_rcp_f32_e32 v131, v131
	v_rcp_f32_e32 v132, v132
	v_rcp_f32_e32 v133, v133
	v_rcp_f32_e32 v134, v134
	v_rcp_f32_e32 v135, v135
	v_rcp_f32_e32 v136, v136
	v_rcp_f32_e32 v137, v137
	v_rcp_f32_e32 v138, v138
	v_mul_f32_e32 v131, v48, v131
	v_mul_f32_e32 v132, v49, v132
	v_mul_f32_e32 v133, v50, v133
	v_mul_f32_e32 v134, v51, v134
	v_mul_f32_e32 v135, v52, v135
	v_mul_f32_e32 v136, v53, v136
	v_mul_f32_e32 v137, v54, v137
	v_mul_f32_e32 v138, v55, v138
	v_mul_f32_e32 v131, v32, v131
	v_mul_f32_e32 v132, v33, v132
	v_mul_f32_e32 v133, v34, v133
	v_mul_f32_e32 v134, v35, v134
	v_mul_f32_e32 v135, v36, v135
	v_mul_f32_e32 v136, v37, v136
	v_mul_f32_e32 v137, v38, v137
	v_mul_f32_e32 v138, v39, v138
	v_add_u32_e32 v48, 64, v128
	v_add_u32_e32 v49, 0x1c40, v128
	v_add_u32_e32 v50, 0x3840, v128
	v_add_u32_e32 v51, 0x5440, v128
	v_add_u32_e32 v52, 0xe040, v128
	v_add_u32_e32 v53, 0xfc40, v128
	v_add_u32_e32 v54, 0x11840, v128
	v_add_u32_e32 v55, 0x13440, v128
	v_cvt_pk_bf16_f32 v139, v131, v132
	v_cvt_pk_bf16_f32 v140, v133, v134
	v_cvt_pk_bf16_f32 v141, v135, v136
	v_cvt_pk_bf16_f32 v142, v137, v138
	global_store_short v48, v139, s[4:5]
	global_store_short_d16_hi v49, v139, s[4:5]
	global_store_short v50, v140, s[4:5]
	global_store_short_d16_hi v51, v140, s[4:5]
	global_store_short v52, v141, s[4:5]
	global_store_short_d16_hi v53, v141, s[4:5]
	global_store_short v54, v142, s[4:5]
	global_store_short_d16_hi v55, v142, s[4:5]
	v_mul_f32_e32 v143, 0xbfb8aa3b, v56
	v_mul_f32_e32 v144, 0xbfb8aa3b, v57
	v_mul_f32_e32 v145, 0xbfb8aa3b, v58
	v_mul_f32_e32 v146, 0xbfb8aa3b, v59
	v_mul_f32_e32 v147, 0xbfb8aa3b, v60
	v_mul_f32_e32 v148, 0xbfb8aa3b, v61
	v_mul_f32_e32 v149, 0xbfb8aa3b, v62
	v_mul_f32_e32 v150, 0xbfb8aa3b, v63
	v_exp_f32_e32 v143, v143
	v_exp_f32_e32 v144, v144
	v_exp_f32_e32 v145, v145
	v_exp_f32_e32 v146, v146
	v_exp_f32_e32 v147, v147
	v_exp_f32_e32 v148, v148
	v_exp_f32_e32 v149, v149
	v_exp_f32_e32 v150, v150
	v_add_f32_e32 v143, 1.0, v143
	v_add_f32_e32 v144, 1.0, v144
	v_add_f32_e32 v145, 1.0, v145
	v_add_f32_e32 v146, 1.0, v146
	v_add_f32_e32 v147, 1.0, v147
	v_add_f32_e32 v148, 1.0, v148
	v_add_f32_e32 v149, 1.0, v149
	v_add_f32_e32 v150, 1.0, v150
	v_rcp_f32_e32 v143, v143
	v_rcp_f32_e32 v144, v144
	v_rcp_f32_e32 v145, v145
	v_rcp_f32_e32 v146, v146
	v_rcp_f32_e32 v147, v147
	v_rcp_f32_e32 v148, v148
	v_rcp_f32_e32 v149, v149
	v_rcp_f32_e32 v150, v150
	v_mul_f32_e32 v143, v56, v143
	v_mul_f32_e32 v144, v57, v144
	v_mul_f32_e32 v145, v58, v145
	v_mul_f32_e32 v146, v59, v146
	v_mul_f32_e32 v147, v60, v147
	v_mul_f32_e32 v148, v61, v148
	v_mul_f32_e32 v149, v62, v149
	v_mul_f32_e32 v150, v63, v150
	v_mul_f32_e32 v143, v40, v143
	v_mul_f32_e32 v144, v41, v144
	v_mul_f32_e32 v145, v42, v145
	v_mul_f32_e32 v146, v43, v146
	v_mul_f32_e32 v147, v44, v147
	v_mul_f32_e32 v148, v45, v148
	v_mul_f32_e32 v149, v46, v149
	v_mul_f32_e32 v150, v47, v150
	v_add_u32_e32 v56, 0x1c040, v128
	v_add_u32_e32 v57, 0x1dc40, v128
	v_add_u32_e32 v58, 0x1f840, v128
	v_add_u32_e32 v59, 0x21440, v128
	v_add_u32_e32 v60, 0x2a040, v128
	v_add_u32_e32 v61, 0x2bc40, v128
	v_add_u32_e32 v62, 0x2d840, v128
	v_add_u32_e32 v63, 0x2f440, v128
	v_cvt_pk_bf16_f32 v151, v143, v144
	v_cvt_pk_bf16_f32 v152, v145, v146
	v_cvt_pk_bf16_f32 v153, v147, v148
	v_cvt_pk_bf16_f32 v154, v149, v150
	global_store_short v56, v151, s[4:5]
	global_store_short_d16_hi v57, v151, s[4:5]
	global_store_short v58, v152, s[4:5]
	global_store_short_d16_hi v59, v152, s[4:5]
	global_store_short v60, v153, s[4:5]
	global_store_short_d16_hi v61, v153, s[4:5]
	global_store_short v62, v154, s[4:5]
	global_store_short_d16_hi v63, v154, s[4:5]
	v_mul_f32_e32 v131, 0xbfb8aa3b, v16
	v_mul_f32_e32 v132, 0xbfb8aa3b, v17
	v_mul_f32_e32 v133, 0xbfb8aa3b, v18
	v_mul_f32_e32 v134, 0xbfb8aa3b, v19
	v_mul_f32_e32 v135, 0xbfb8aa3b, v20
	v_mul_f32_e32 v136, 0xbfb8aa3b, v21
	v_mul_f32_e32 v137, 0xbfb8aa3b, v22
	v_mul_f32_e32 v138, 0xbfb8aa3b, v23
	v_exp_f32_e32 v131, v131
	v_exp_f32_e32 v132, v132
	v_exp_f32_e32 v133, v133
	v_exp_f32_e32 v134, v134
	v_exp_f32_e32 v135, v135
	v_exp_f32_e32 v136, v136
	v_exp_f32_e32 v137, v137
	v_exp_f32_e32 v138, v138
	v_add_f32_e32 v131, 1.0, v131
	v_add_f32_e32 v132, 1.0, v132
	v_add_f32_e32 v133, 1.0, v133
	v_add_f32_e32 v134, 1.0, v134
	v_add_f32_e32 v135, 1.0, v135
	v_add_f32_e32 v136, 1.0, v136
	v_add_f32_e32 v137, 1.0, v137
	v_add_f32_e32 v138, 1.0, v138
	v_rcp_f32_e32 v131, v131
	v_rcp_f32_e32 v132, v132
	v_rcp_f32_e32 v133, v133
	v_rcp_f32_e32 v134, v134
	v_rcp_f32_e32 v135, v135
	v_rcp_f32_e32 v136, v136
	v_rcp_f32_e32 v137, v137
	v_rcp_f32_e32 v138, v138
	v_mul_f32_e32 v131, v16, v131
	v_mul_f32_e32 v132, v17, v132
	v_mul_f32_e32 v133, v18, v133
	v_mul_f32_e32 v134, v19, v134
	v_mul_f32_e32 v135, v20, v135
	v_mul_f32_e32 v136, v21, v136
	v_mul_f32_e32 v137, v22, v137
	v_mul_f32_e32 v138, v23, v138
	v_mul_f32_e32 v131, v0, v131
	v_mul_f32_e32 v132, v1, v132
	v_mul_f32_e32 v133, v2, v133
	v_mul_f32_e32 v134, v3, v134
	v_mul_f32_e32 v135, v4, v135
	v_mul_f32_e32 v136, v5, v136
	v_mul_f32_e32 v137, v6, v137
	v_mul_f32_e32 v138, v7, v138
	v_add_u32_e32 v16, 0x38040, v128
	v_add_u32_e32 v17, 0x39c40, v128
	v_add_u32_e32 v18, 0x3b840, v128
	v_add_u32_e32 v19, 0x3d440, v128
	v_add_u32_e32 v20, 0x46040, v128
	v_add_u32_e32 v21, 0x47c40, v128
	v_add_u32_e32 v22, 0x49840, v128
	v_add_u32_e32 v23, 0x4b440, v128
	v_cvt_pk_bf16_f32 v139, v131, v132
	v_cvt_pk_bf16_f32 v140, v133, v134
	v_cvt_pk_bf16_f32 v141, v135, v136
	v_cvt_pk_bf16_f32 v142, v137, v138
	global_store_short v16, v139, s[4:5]
	global_store_short_d16_hi v17, v139, s[4:5]
	global_store_short v18, v140, s[4:5]
	global_store_short_d16_hi v19, v140, s[4:5]
	global_store_short v20, v141, s[4:5]
	global_store_short_d16_hi v21, v141, s[4:5]
	global_store_short v22, v142, s[4:5]
	global_store_short_d16_hi v23, v142, s[4:5]
	v_mul_f32_e32 v143, 0xbfb8aa3b, v24
	v_mul_f32_e32 v144, 0xbfb8aa3b, v25
	v_mul_f32_e32 v145, 0xbfb8aa3b, v26
	v_mul_f32_e32 v146, 0xbfb8aa3b, v27
	v_mul_f32_e32 v147, 0xbfb8aa3b, v28
	v_mul_f32_e32 v148, 0xbfb8aa3b, v29
	v_mul_f32_e32 v149, 0xbfb8aa3b, v30
	v_mul_f32_e32 v150, 0xbfb8aa3b, v31
	v_exp_f32_e32 v143, v143
	v_exp_f32_e32 v144, v144
	v_exp_f32_e32 v145, v145
	v_exp_f32_e32 v146, v146
	v_exp_f32_e32 v147, v147
	v_exp_f32_e32 v148, v148
	v_exp_f32_e32 v149, v149
	v_exp_f32_e32 v150, v150
	v_add_f32_e32 v143, 1.0, v143
	v_add_f32_e32 v144, 1.0, v144
	v_add_f32_e32 v145, 1.0, v145
	v_add_f32_e32 v146, 1.0, v146
	v_add_f32_e32 v147, 1.0, v147
	v_add_f32_e32 v148, 1.0, v148
	v_add_f32_e32 v149, 1.0, v149
	v_add_f32_e32 v150, 1.0, v150
	v_rcp_f32_e32 v143, v143
	v_rcp_f32_e32 v144, v144
	v_rcp_f32_e32 v145, v145
	v_rcp_f32_e32 v146, v146
	v_rcp_f32_e32 v147, v147
	v_rcp_f32_e32 v148, v148
	v_rcp_f32_e32 v149, v149
	v_rcp_f32_e32 v150, v150
	v_mul_f32_e32 v143, v24, v143
	v_mul_f32_e32 v144, v25, v144
	v_mul_f32_e32 v145, v26, v145
	v_mul_f32_e32 v146, v27, v146
	v_mul_f32_e32 v147, v28, v147
	v_mul_f32_e32 v148, v29, v148
	v_mul_f32_e32 v149, v30, v149
	v_mul_f32_e32 v150, v31, v150
	v_mul_f32_e32 v143, v8, v143
	v_mul_f32_e32 v144, v9, v144
	v_mul_f32_e32 v145, v10, v145
	v_mul_f32_e32 v146, v11, v146
	v_mul_f32_e32 v147, v12, v147
	v_mul_f32_e32 v148, v13, v148
	v_mul_f32_e32 v149, v14, v149
	v_mul_f32_e32 v150, v15, v150
	v_add_u32_e32 v24, 0x54040, v128
	v_add_u32_e32 v25, 0x55c40, v128
	v_add_u32_e32 v26, 0x57840, v128
	v_add_u32_e32 v27, 0x59440, v128
	v_add_u32_e32 v28, 0x62040, v128
	v_add_u32_e32 v29, 0x63c40, v128
	v_add_u32_e32 v30, 0x65840, v128
	v_add_u32_e32 v31, 0x67440, v128
	v_cvt_pk_bf16_f32 v151, v143, v144
	v_cvt_pk_bf16_f32 v152, v145, v146
	v_cvt_pk_bf16_f32 v153, v147, v148
	v_cvt_pk_bf16_f32 v154, v149, v150
	global_store_short v24, v151, s[4:5]
	global_store_short_d16_hi v25, v151, s[4:5]
	global_store_short v26, v152, s[4:5]
	global_store_short_d16_hi v27, v152, s[4:5]
	global_store_short v28, v153, s[4:5]
	global_store_short_d16_hi v29, v153, s[4:5]
	global_store_short v30, v154, s[4:5]
	global_store_short_d16_hi v31, v154, s[4:5]
	s_add_i32 s30, s30, s85
	s_cmp_ge_i32 s30, s20
	s_cbranch_scc1 .LBB0_905
.LBB0_897:
	s_abs_i32 s3, s30
	s_mul_hi_u32 s12, s3, s29
	s_mul_i32 s13, s12, s26
	s_ashr_i32 s2, s30, 31
	s_sub_i32 s3, s3, s13
	s_xor_b32 s2, s2, s28
	s_add_i32 s13, s12, 1
	s_sub_i32 s14, s3, s26
	s_cmp_ge_u32 s3, s26
	s_cselect_b32 s12, s13, s12
	s_cselect_b32 s3, s14, s3
	s_add_i32 s13, s12, 1
	s_cmp_ge_u32 s3, s26
	s_cselect_b32 s3, s13, s12
	s_xor_b32 s3, s3, s2
	s_sub_i32 s2, s3, s2
	s_mul_i32 s3, s2, s19
	s_sub_i32 s3, s30, s3
	s_lshl_b32 s12, s3, 5
	v_mov_b32_e32 v181, v216
	s_and_b32 s31, s12, 0xffffff80
	s_lshl_b32 s3, s3, 8
	v_ashrrev_i32_e32 v2, 2, v181
	v_add_u32_e32 v3, s31, v2
	v_lshlrev_b32_e32 v0, 4, v181
	v_and_b32_e32 v4, 48, v0
	v_min_i32_e32 v0, s27, v3
	v_ashrrev_i32_e32 v1, 31, v0
	v_lshl_add_u64 v[0:1], v[0:1], 2, s[0:1]
	s_lshl_b32 s2, s2, 10
	s_and_b32 s3, s3, 0x300
	s_or_b32 s34, s3, s2
	v_and_b32_e32 v183, 31, v181
	s_mov_b32 s35, 0
	s_waitcnt vmcnt(63)
	v_lshlrev_b32_e32 v0, 10, v163
	v_and_or_b32 v180, v0, s83, v4
	v_add_u32_e32 v0, 64, v3
	v_min_i32_e32 v0, s27, v0
	v_ashrrev_i32_e32 v1, 31, v0
	v_lshl_add_u64 v[0:1], v[0:1], 2, s[0:1]
	v_lshlrev_b32_e32 v0, 10, v164
	v_and_or_b32 v182, v0, s83, v4
	v_add_u32_e32 v0, s34, v2
	v_lshl_or_b32 v178, v0, 11, v4
	v_add_u32_e32 v0, 0x20000, v178
	v_add_u32_e32 v1, 0x40000, v178
	v_add_u32_e32 v3, 0x60000, v178
	v_mul_lo_u32 v0, v2, s74
	v_add_u32_e32 v188, v4, v0
	v_or_b32_e32 v0, 64, v180
	v_lshl_add_u64 v[186:187], s[10:11], 0, v[178:179]
	s_waitcnt vmcnt(0)
	s_waitcnt vmcnt(0)
	s_waitcnt vmcnt(0)
	s_waitcnt vmcnt(0)
	s_waitcnt vmcnt(0)
	s_waitcnt vmcnt(0)
	v_or_b32_e32 v0, 64, v182
	v_add_u32_e32 v0, 0x20040, v178
	v_add_u32_e32 v0, 0x40040, v178
	v_add_u32_e32 v0, 0x60040, v178
	v_ashrrev_i32_e32 v0, 1, v181
	v_and_b32_e32 v189, 0xffffffc0, v0
	v_lshrrev_b32_e32 v0, 1, v181
	v_or_b32_e32 v1, v189, v183
	v_and_b32_e32 v0, 16, v0
	v_mad_u64_u32 v[184:185], s[2:3], v1, s74, v[0:1]
	v_lshlrev_b32_e32 v1, 1, v181
	v_and_b32_e32 v185, 0x80, v1
	v_or_b32_e32 v1, v185, v183
	v_mul_u32_u24_e32 v1, 40, v1
	v_lshl_add_u32 v190, v1, 1, v0
	v_mov_b32_e32 v0, 0
	s_mov_b64 s[2:3], 0
	v_mov_b32_e32 v1, v0
	v_mov_b32_e32 v2, v0
	v_mov_b32_e32 v3, v0
	v_mov_b32_e32 v4, v0
	v_mov_b32_e32 v5, v0
	v_mov_b32_e32 v6, v0
	v_mov_b32_e32 v7, v0
	v_mov_b32_e32 v8, v0
	v_mov_b32_e32 v9, v0
	v_mov_b32_e32 v10, v0
	v_mov_b32_e32 v11, v0
	v_mov_b32_e32 v12, v0
	v_mov_b32_e32 v13, v0
	v_mov_b32_e32 v14, v0
	v_mov_b32_e32 v15, v0
	v_mov_b32_e32 v16, v0
	v_mov_b32_e32 v17, v0
	v_mov_b32_e32 v18, v0
	v_mov_b32_e32 v19, v0
	v_mov_b32_e32 v20, v0
	v_mov_b32_e32 v21, v0
	v_mov_b32_e32 v22, v0
	v_mov_b32_e32 v23, v0
	v_mov_b32_e32 v24, v0
	v_mov_b32_e32 v25, v0
	v_mov_b32_e32 v26, v0
	v_mov_b32_e32 v27, v0
	v_mov_b32_e32 v28, v0
	v_mov_b32_e32 v29, v0
	v_mov_b32_e32 v30, v0
	v_mov_b32_e32 v31, v0
	v_mov_b32_e32 v64, v0
	v_mov_b32_e32 v65, v0
	v_mov_b32_e32 v66, v0
	v_mov_b32_e32 v67, v0
	v_mov_b32_e32 v68, v0
	v_mov_b32_e32 v69, v0
	v_mov_b32_e32 v70, v0
	v_mov_b32_e32 v71, v0
	v_mov_b32_e32 v72, v0
	v_mov_b32_e32 v73, v0
	v_mov_b32_e32 v74, v0
	v_mov_b32_e32 v75, v0
	v_mov_b32_e32 v76, v0
	v_mov_b32_e32 v77, v0
	v_mov_b32_e32 v78, v0
	v_mov_b32_e32 v79, v0
	v_mov_b32_e32 v80, v0
	v_mov_b32_e32 v81, v0
	v_mov_b32_e32 v82, v0
	v_mov_b32_e32 v83, v0
	v_mov_b32_e32 v84, v0
	v_mov_b32_e32 v85, v0
	v_mov_b32_e32 v86, v0
	v_mov_b32_e32 v87, v0
	v_mov_b32_e32 v88, v0
	v_mov_b32_e32 v89, v0
	v_mov_b32_e32 v90, v0
	v_mov_b32_e32 v91, v0
	v_mov_b32_e32 v92, v0
	v_mov_b32_e32 v93, v0
	v_mov_b32_e32 v94, v0
	v_mov_b32_e32 v95, v0
	v_mov_b32_e32 v32, v0
	v_mov_b32_e32 v33, v0
	v_mov_b32_e32 v34, v0
	v_mov_b32_e32 v35, v0
	v_mov_b32_e32 v36, v0
	v_mov_b32_e32 v37, v0
	v_mov_b32_e32 v38, v0
	v_mov_b32_e32 v39, v0
	v_mov_b32_e32 v40, v0
	v_mov_b32_e32 v41, v0
	v_mov_b32_e32 v42, v0
	v_mov_b32_e32 v43, v0
	v_mov_b32_e32 v44, v0
	v_mov_b32_e32 v45, v0
	v_mov_b32_e32 v46, v0
	v_mov_b32_e32 v47, v0
	v_mov_b32_e32 v48, v0
	v_mov_b32_e32 v49, v0
	v_mov_b32_e32 v50, v0
	v_mov_b32_e32 v51, v0
	v_mov_b32_e32 v52, v0
	v_mov_b32_e32 v53, v0
	v_mov_b32_e32 v54, v0
	v_mov_b32_e32 v55, v0
	v_mov_b32_e32 v56, v0
	v_mov_b32_e32 v57, v0
	v_mov_b32_e32 v58, v0
	v_mov_b32_e32 v59, v0
	v_mov_b32_e32 v60, v0
	v_mov_b32_e32 v61, v0
	v_mov_b32_e32 v62, v0
	v_mov_b32_e32 v63, v0
	v_mov_b32_e32 v96, v0
	v_mov_b32_e32 v97, v0
	v_mov_b32_e32 v98, v0
	v_mov_b32_e32 v99, v0
	v_mov_b32_e32 v100, v0
	v_mov_b32_e32 v101, v0
	v_mov_b32_e32 v102, v0
	v_mov_b32_e32 v103, v0
	v_mov_b32_e32 v104, v0
	v_mov_b32_e32 v105, v0
	v_mov_b32_e32 v106, v0
	v_mov_b32_e32 v107, v0
	v_mov_b32_e32 v108, v0
	v_mov_b32_e32 v109, v0
	v_mov_b32_e32 v110, v0
	v_mov_b32_e32 v111, v0
	v_mov_b32_e32 v112, v0
	v_mov_b32_e32 v113, v0
	v_mov_b32_e32 v114, v0
	v_mov_b32_e32 v115, v0
	v_mov_b32_e32 v116, v0
	v_mov_b32_e32 v117, v0
	v_mov_b32_e32 v118, v0
	v_mov_b32_e32 v119, v0
	v_mov_b32_e32 v120, v0
	v_mov_b32_e32 v121, v0
	v_mov_b32_e32 v122, v0
	v_mov_b32_e32 v123, v0
	v_mov_b32_e32 v124, v0
	v_mov_b32_e32 v125, v0
	v_mov_b32_e32 v126, v0
	v_mov_b32_e32 v127, v0
	v_and_b32_e32 v137, 3, v216
	v_bfe_u32 v138, v216, 4, 2
	v_xor_b32_e32 v138, v137, v138
	v_sub_u32_e32 v138, v138, v137
	v_lshlrev_b32_e32 v136, 4, v138
	v_lshrrev_b32_e32 v137, 6, v216
	v_lshlrev_b32_e32 v138, 10, v137
	v_and_b32_e32 v139, 31, v216
	v_bfe_u32 v140, v216, 5, 1
	v_readfirstlane_b32 s14, v138
	v_bfe_u32 v141, v139, 2, 2
	v_lshrrev_b32_e32 v142, 1, v137
	v_and_b32_e32 v143, 1, v137
	v_lshl_add_u32 v142, v142, 6, v139
	v_lshl_add_u32 v143, v143, 7, v139
	v_lshlrev_b32_e32 v142, 6, v142
	v_lshlrev_b32_e32 v143, 6, v143
	v_add_u32_e32 v143, 0x4000, v143
	v_or_b32_e32 v144, 0, v140
	v_xor_b32_e32 v144, v144, v141
	v_lshl_add_u32 v128, v144, 4, v142
	v_lshl_add_u32 v130, v144, 4, v143
	v_or_b32_e32 v144, 2, v140
	v_xor_b32_e32 v144, v144, v141
	v_lshl_add_u32 v129, v144, 4, v142
	v_lshl_add_u32 v131, v144, 4, v143
	v_add_u32_e32 v193, s2, v180
	v_add_u32_e32 v192, s2, v182
	v_add_u32_e32 v191, s2, v178
	v_add_u32_e32 v132, v193, v136
	v_add_u32_e32 v133, v192, v136
	v_add_u32_e32 v134, v191, v136
	s_add_u32 m0, s14, 0x0
	v_add_u32_e32 v135, 0x0, v132
	global_load_lds_dwordx4 v135, s[6:7]
	s_add_u32 m0, s14, 0x1000
	v_add_u32_e32 v135, 0x0, v133
	global_load_lds_dwordx4 v135, s[6:7]
	s_add_u32 m0, s14, 0x4000
	v_add_u32_e32 v135, 0x0, v134
	global_load_lds_dwordx4 v135, s[8:9]
	s_add_u32 m0, s14, 0x5000
	v_add_u32_e32 v135, 0x20000, v134
	global_load_lds_dwordx4 v135, s[8:9]
	s_add_u32 m0, s14, 0x6000
	v_add_u32_e32 v135, 0x40000, v134
	global_load_lds_dwordx4 v135, s[8:9]
	s_add_u32 m0, s14, 0x7000
	v_add_u32_e32 v135, 0x60000, v134
	global_load_lds_dwordx4 v135, s[8:9]
	s_waitcnt vmcnt(0) lgkmcnt(0)
	s_barrier
	s_branch .Ldmaq19167_loop

.LBB0_905:
	s_waitcnt vmcnt(0)
	s_lshl_b32 s25, s25, 1
	s_cmp_ge_i32 s47, s25
	s_cbranch_scc1 .LBB0_916
	v_readlane_b32 s0, v254, 2
	s_add_u32 s0, s23, s0
	s_addc_u32 s1, s24, 0
	s_abs_i32 s26, s19
	v_cvt_f32_u32_e32 v0, s26
	s_sub_i32 s2, 0, s26
	s_add_i32 s23, s16, -1
	s_ashr_i32 s24, s19, 31
	v_rcp_iflag_f32_e32 v0, v0
	s_nop 0
	v_mul_f32_e32 v0, 0x4f7ffffe, v0
	v_cvt_u32_f32_e32 v0, v0
	s_nop 0
	v_readfirstlane_b32 s3, v0
	s_mul_i32 s2, s2, s3
	s_mul_hi_u32 s2, s3, s2
	s_add_i32 s27, s3, s2
	v_readlane_b32 s2, v254, 41
	s_add_u32 s10, s21, s2
	v_readlane_b32 s2, v254, 42
	s_addc_u32 s11, s22, s2
	v_readlane_b32 s21, v254, 43
	s_mov_b32 s22, s47
	s_branch .LBB0_908
